# GEMM loops: removed redundant adjacent s_setprio 0/1 pairs between MFMA clusters
# speedup vs baseline: 1.0106x; 1.0106x over previous
.LBB0_822:
	s_add_u32 s24, s30, 0xfff80080
	s_addc_u32 s25, s31, -1
	s_add_i32 s26, 0, 0x10000
	s_cmp_eq_u32 s58, 28
	s_cselect_b32 s35, s41, s25
	s_cselect_b32 s34, s54, s24
	v_add_u32_e32 v140, s26, v155
	s_cselect_b32 s25, s39, s57
	s_cselect_b32 s24, s55, s56
	s_add_i32 s59, 0, 0x14000
	ds_read_b128 v[136:139], v140
	ds_read_b128 v[158:161], v140 offset:1024
	ds_read_b128 v[172:175], v140 offset:2048
	ds_read_b128 v[192:195], v140 offset:3072
	v_add_u32_e32 v140, s59, v155
	ds_read_b128 v[196:199], v140
	ds_read_b128 v[200:203], v140 offset:1024
	ds_read_b128 v[204:207], v140 offset:2048
	ds_read_b128 v[208:211], v140 offset:3072
	v_lshl_add_u64 v[140:141], s[30:31], 0, v[150:151]
	s_add_i32 m0, s29, 0xc000
	ds_read_b128 v[212:215], v163
	ds_read_b128 v[216:219], v163 offset:1024
	ds_read_b128 v[220:223], v163 offset:2048
	ds_read_b128 v[224:227], v163 offset:3072
	ds_read_b128 v[228:231], v163 offset:4096
	ds_read_b128 v[232:235], v163 offset:5120
	ds_read_b128 v[236:239], v163 offset:6144
	ds_read_b128 v[240:243], v163 offset:7168
	global_load_lds_dwordx4 v[140:141], off
	v_lshl_add_u64 v[140:141], s[30:31], 0, v[152:153]
	s_add_i32 m0, s29, 0xe000
	s_nop 0
	global_load_lds_dwordx4 v[140:141], off
	s_waitcnt vmcnt(8)
	s_waitcnt lgkmcnt(0)
	s_barrier
	s_setprio 1
	s_waitcnt lgkmcnt(0)
	v_mfma_f32_16x16x32_bf16 v[132:135], v[136:139], v[212:215], v[132:135]
	v_mfma_f32_16x16x32_bf16 v[128:131], v[172:175], v[212:215], v[128:131]
	v_mfma_f32_16x16x32_bf16 v[116:119], v[136:139], v[220:223], v[116:119]
	v_mfma_f32_16x16x32_bf16 v[112:115], v[172:175], v[220:223], v[112:115]
	v_mfma_f32_16x16x32_bf16 v[100:103], v[136:139], v[228:231], v[100:103]
	v_mfma_f32_16x16x32_bf16 v[96:99], v[172:175], v[228:231], v[96:99]
	v_mfma_f32_16x16x32_bf16 v[84:87], v[136:139], v[236:239], v[84:87]
	v_mfma_f32_16x16x32_bf16 v[80:83], v[172:175], v[236:239], v[80:83]
	v_mfma_f32_16x16x32_bf16 v[132:135], v[158:161], v[216:219], v[132:135]
	v_mfma_f32_16x16x32_bf16 v[128:131], v[192:195], v[216:219], v[128:131]
	v_mfma_f32_16x16x32_bf16 v[116:119], v[158:161], v[224:227], v[116:119]
	v_mfma_f32_16x16x32_bf16 v[112:115], v[192:195], v[224:227], v[112:115]
	v_mfma_f32_16x16x32_bf16 v[100:103], v[158:161], v[232:235], v[100:103]
	v_mfma_f32_16x16x32_bf16 v[96:99], v[192:195], v[232:235], v[96:99]
	v_mfma_f32_16x16x32_bf16 v[84:87], v[158:161], v[240:243], v[84:87]
	v_mfma_f32_16x16x32_bf16 v[80:83], v[192:195], v[240:243], v[80:83]
	v_mfma_f32_16x16x32_bf16 v[124:127], v[196:199], v[212:215], v[124:127]
	v_mfma_f32_16x16x32_bf16 v[120:123], v[204:207], v[212:215], v[120:123]
	v_mfma_f32_16x16x32_bf16 v[108:111], v[196:199], v[220:223], v[108:111]
	v_mfma_f32_16x16x32_bf16 v[104:107], v[204:207], v[220:223], v[104:107]
	v_mfma_f32_16x16x32_bf16 v[92:95], v[196:199], v[228:231], v[92:95]
	v_mfma_f32_16x16x32_bf16 v[88:91], v[204:207], v[228:231], v[88:91]
	v_mfma_f32_16x16x32_bf16 v[76:79], v[196:199], v[236:239], v[76:79]
	v_mfma_f32_16x16x32_bf16 v[72:75], v[204:207], v[236:239], v[72:75]
	v_mfma_f32_16x16x32_bf16 v[124:127], v[200:203], v[216:219], v[124:127]
	v_mfma_f32_16x16x32_bf16 v[120:123], v[208:211], v[216:219], v[120:123]
	v_mfma_f32_16x16x32_bf16 v[108:111], v[200:203], v[224:227], v[108:111]
	v_mfma_f32_16x16x32_bf16 v[104:107], v[208:211], v[224:227], v[104:107]
	v_mfma_f32_16x16x32_bf16 v[92:95], v[200:203], v[232:235], v[92:95]
	v_mfma_f32_16x16x32_bf16 v[88:91], v[208:211], v[232:235], v[88:91]
	v_mfma_f32_16x16x32_bf16 v[76:79], v[200:203], v[240:243], v[76:79]
	v_mfma_f32_16x16x32_bf16 v[72:75], v[208:211], v[240:243], v[72:75]
	s_setprio 0
	s_barrier
	s_add_i32 s26, s26, s22
	v_lshl_add_u64 v[140:141], s[24:25], 0, v[146:147]
	s_mov_b32 m0, s26
	ds_read_b128 v[212:215], v163 offset:16384
	ds_read_b128 v[216:219], v163 offset:17408
	ds_read_b128 v[220:223], v163 offset:18432
	ds_read_b128 v[224:227], v163 offset:19456
	ds_read_b128 v[228:231], v163 offset:20480
	ds_read_b128 v[232:235], v163 offset:21504
	ds_read_b128 v[236:239], v163 offset:22528
	ds_read_b128 v[240:243], v163 offset:23552
	global_load_lds_dwordx4 v[140:141], off
	s_add_i32 m0, s26, 0x2000
	s_add_u32 s68, s24, 0x80000
	v_lshl_add_u64 v[142:143], s[24:25], 0, v[34:35]
	s_addc_u32 s69, s25, 0
	s_add_i32 s26, s59, s22
	global_load_lds_dwordx4 v[142:143], off
	v_lshl_add_u64 v[168:169], s[68:69], 0, v[146:147]
	s_mov_b32 m0, s26
	v_lshl_add_u64 v[176:177], s[34:35], 0, v[144:145]
	global_load_lds_dwordx4 v[168:169], off
	v_lshl_add_u64 v[168:169], s[68:69], 0, v[34:35]
	s_add_i32 m0, s26, 0x2000
	s_nop 0
	global_load_lds_dwordx4 v[168:169], off
	v_lshl_add_u64 v[168:169], s[34:35], 0, v[148:149]
	s_mov_b32 m0, s29
	s_nop 0
	global_load_lds_dwordx4 v[168:169], off
	s_mov_b32 m0, s47
	s_nop 0
	global_load_lds_dwordx4 v[176:177], off
	s_waitcnt vmcnt(8)
	s_waitcnt lgkmcnt(0)
	s_barrier
	s_setprio 1
	s_waitcnt lgkmcnt(0)
	v_mfma_f32_16x16x32_bf16 v[68:71], v[136:139], v[212:215], v[68:71]
	v_mfma_f32_16x16x32_bf16 v[64:67], v[172:175], v[212:215], v[64:67]
	v_mfma_f32_16x16x32_bf16 v[52:55], v[136:139], v[220:223], v[52:55]
	v_mfma_f32_16x16x32_bf16 v[48:51], v[172:175], v[220:223], v[48:51]
	v_mfma_f32_16x16x32_bf16 v[28:31], v[136:139], v[228:231], v[28:31]
	v_mfma_f32_16x16x32_bf16 v[24:27], v[172:175], v[228:231], v[24:27]
	v_mfma_f32_16x16x32_bf16 v[12:15], v[136:139], v[236:239], v[12:15]
	v_mfma_f32_16x16x32_bf16 v[8:11], v[172:175], v[236:239], v[8:11]
	v_mfma_f32_16x16x32_bf16 v[68:71], v[158:161], v[216:219], v[68:71]
	v_mfma_f32_16x16x32_bf16 v[64:67], v[192:195], v[216:219], v[64:67]
	v_mfma_f32_16x16x32_bf16 v[52:55], v[158:161], v[224:227], v[52:55]
	v_mfma_f32_16x16x32_bf16 v[48:51], v[192:195], v[224:227], v[48:51]
	v_mfma_f32_16x16x32_bf16 v[28:31], v[158:161], v[232:235], v[28:31]
	v_mfma_f32_16x16x32_bf16 v[24:27], v[192:195], v[232:235], v[24:27]
	v_mfma_f32_16x16x32_bf16 v[12:15], v[158:161], v[240:243], v[12:15]
	v_mfma_f32_16x16x32_bf16 v[8:11], v[192:195], v[240:243], v[8:11]
	v_mfma_f32_16x16x32_bf16 v[60:63], v[196:199], v[212:215], v[60:63]
	v_mfma_f32_16x16x32_bf16 v[56:59], v[204:207], v[212:215], v[56:59]
	v_mfma_f32_16x16x32_bf16 v[44:47], v[196:199], v[220:223], v[44:47]
	v_mfma_f32_16x16x32_bf16 v[40:43], v[204:207], v[220:223], v[40:43]
	v_mfma_f32_16x16x32_bf16 v[20:23], v[196:199], v[228:231], v[20:23]
	v_mfma_f32_16x16x32_bf16 v[16:19], v[204:207], v[228:231], v[16:19]
	v_mfma_f32_16x16x32_bf16 v[4:7], v[196:199], v[236:239], v[4:7]
	v_mfma_f32_16x16x32_bf16 v[0:3], v[204:207], v[236:239], v[0:3]
	v_mfma_f32_16x16x32_bf16 v[60:63], v[200:203], v[216:219], v[60:63]
	v_mfma_f32_16x16x32_bf16 v[56:59], v[208:211], v[216:219], v[56:59]
	v_mfma_f32_16x16x32_bf16 v[44:47], v[200:203], v[224:227], v[44:47]
	v_mfma_f32_16x16x32_bf16 v[40:43], v[208:211], v[224:227], v[40:43]
	v_mfma_f32_16x16x32_bf16 v[20:23], v[200:203], v[232:235], v[20:23]
	v_mfma_f32_16x16x32_bf16 v[16:19], v[208:211], v[232:235], v[16:19]
	v_mfma_f32_16x16x32_bf16 v[4:7], v[200:203], v[240:243], v[4:7]
	v_mfma_f32_16x16x32_bf16 v[0:3], v[208:211], v[240:243], v[0:3]
	s_setprio 0
	s_barrier
	s_add_i32 s26, 0, 0x18000
	v_add_u32_e32 v154, s26, v155
	s_add_i32 s59, 0, 0x1c000
	ds_read_b128 v[136:139], v154
	ds_read_b128 v[158:161], v154 offset:1024
	ds_read_b128 v[172:175], v154 offset:2048
	ds_read_b128 v[192:195], v154 offset:3072
	v_add_u32_e32 v154, s59, v155
	ds_read_b128 v[196:199], v154
	ds_read_b128 v[200:203], v154 offset:1024
	ds_read_b128 v[204:207], v154 offset:2048
	ds_read_b128 v[208:211], v154 offset:3072
	s_add_u32 s34, s34, 0x80000
	s_addc_u32 s35, s35, 0
	s_mov_b32 m0, s48
	v_lshl_add_u64 v[244:245], s[34:35], 0, v[148:149]
	ds_read_b128 v[212:215], v163 offset:32768
	ds_read_b128 v[216:219], v163 offset:33792
	ds_read_b128 v[220:223], v163 offset:34816
	ds_read_b128 v[224:227], v163 offset:35840
	ds_read_b128 v[228:231], v163 offset:36864
	ds_read_b128 v[232:235], v163 offset:37888
	ds_read_b128 v[236:239], v163 offset:38912
	ds_read_b128 v[240:243], v163 offset:39936
	global_load_lds_dwordx4 v[244:245], off
	v_lshl_add_u64 v[244:245], s[34:35], 0, v[144:145]
	s_mov_b32 m0, s49
	s_nop 0
	global_load_lds_dwordx4 v[244:245], off
	s_waitcnt vmcnt(8)
	s_waitcnt lgkmcnt(0)
	s_barrier
	s_setprio 1
	s_waitcnt lgkmcnt(0)
	v_mfma_f32_16x16x32_bf16 v[132:135], v[136:139], v[212:215], v[132:135]
	v_mfma_f32_16x16x32_bf16 v[128:131], v[172:175], v[212:215], v[128:131]
	v_mfma_f32_16x16x32_bf16 v[116:119], v[136:139], v[220:223], v[116:119]
	v_mfma_f32_16x16x32_bf16 v[112:115], v[172:175], v[220:223], v[112:115]
	v_mfma_f32_16x16x32_bf16 v[100:103], v[136:139], v[228:231], v[100:103]
	v_mfma_f32_16x16x32_bf16 v[96:99], v[172:175], v[228:231], v[96:99]
	v_mfma_f32_16x16x32_bf16 v[84:87], v[136:139], v[236:239], v[84:87]
	v_mfma_f32_16x16x32_bf16 v[80:83], v[172:175], v[236:239], v[80:83]
	v_mfma_f32_16x16x32_bf16 v[132:135], v[158:161], v[216:219], v[132:135]
	v_mfma_f32_16x16x32_bf16 v[128:131], v[192:195], v[216:219], v[128:131]
	v_mfma_f32_16x16x32_bf16 v[116:119], v[158:161], v[224:227], v[116:119]
	v_mfma_f32_16x16x32_bf16 v[112:115], v[192:195], v[224:227], v[112:115]
	v_mfma_f32_16x16x32_bf16 v[100:103], v[158:161], v[232:235], v[100:103]
	v_mfma_f32_16x16x32_bf16 v[96:99], v[192:195], v[232:235], v[96:99]
	v_mfma_f32_16x16x32_bf16 v[84:87], v[158:161], v[240:243], v[84:87]
	v_mfma_f32_16x16x32_bf16 v[80:83], v[192:195], v[240:243], v[80:83]
	v_mfma_f32_16x16x32_bf16 v[124:127], v[196:199], v[212:215], v[124:127]
	v_mfma_f32_16x16x32_bf16 v[120:123], v[204:207], v[212:215], v[120:123]
	v_mfma_f32_16x16x32_bf16 v[108:111], v[196:199], v[220:223], v[108:111]
	v_mfma_f32_16x16x32_bf16 v[104:107], v[204:207], v[220:223], v[104:107]
	v_mfma_f32_16x16x32_bf16 v[92:95], v[196:199], v[228:231], v[92:95]
	v_mfma_f32_16x16x32_bf16 v[88:91], v[204:207], v[228:231], v[88:91]
	v_mfma_f32_16x16x32_bf16 v[76:79], v[196:199], v[236:239], v[76:79]
	v_mfma_f32_16x16x32_bf16 v[72:75], v[204:207], v[236:239], v[72:75]
	v_mfma_f32_16x16x32_bf16 v[124:127], v[200:203], v[216:219], v[124:127]
	v_mfma_f32_16x16x32_bf16 v[120:123], v[208:211], v[216:219], v[120:123]
	v_mfma_f32_16x16x32_bf16 v[108:111], v[200:203], v[224:227], v[108:111]
	v_mfma_f32_16x16x32_bf16 v[104:107], v[208:211], v[224:227], v[104:107]
	v_mfma_f32_16x16x32_bf16 v[92:95], v[200:203], v[232:235], v[92:95]
	v_mfma_f32_16x16x32_bf16 v[88:91], v[208:211], v[232:235], v[88:91]
	v_mfma_f32_16x16x32_bf16 v[76:79], v[200:203], v[240:243], v[76:79]
	v_mfma_f32_16x16x32_bf16 v[72:75], v[208:211], v[240:243], v[72:75]
	s_setprio 0
	s_barrier
	s_add_i32 s26, s26, s22
	v_lshl_add_u64 v[140:141], v[140:141], 0, s[60:61]
	s_mov_b32 m0, s26
	ds_read_b128 v[212:215], v163 offset:49152
	ds_read_b128 v[216:219], v163 offset:50176
	ds_read_b128 v[220:223], v163 offset:51200
	ds_read_b128 v[224:227], v163 offset:52224
	ds_read_b128 v[228:231], v163 offset:53248
	ds_read_b128 v[232:235], v163 offset:54272
	ds_read_b128 v[236:239], v163 offset:55296
	ds_read_b128 v[240:243], v163 offset:56320
	global_load_lds_dwordx4 v[140:141], off
	s_add_i32 m0, s26, 0x2000
	s_add_u32 s24, s24, 0x80080
	v_lshl_add_u64 v[140:141], v[142:143], 0, s[60:61]
	s_addc_u32 s25, s25, 0
	s_add_i32 s26, s59, s22
	global_load_lds_dwordx4 v[140:141], off
	v_lshl_add_u64 v[140:141], s[24:25], 0, v[146:147]
	s_mov_b32 m0, s26
	s_nop 0
	global_load_lds_dwordx4 v[140:141], off
	v_lshl_add_u64 v[140:141], s[24:25], 0, v[34:35]
	s_add_i32 m0, s26, 0x2000
	s_nop 0
	global_load_lds_dwordx4 v[140:141], off
	v_lshl_add_u64 v[140:141], v[168:169], 0, s[60:61]
	s_mov_b32 m0, s50
	s_nop 0
	global_load_lds_dwordx4 v[140:141], off
	v_lshl_add_u64 v[140:141], v[176:177], 0, s[60:61]
	s_mov_b32 m0, s51
	s_nop 0
	global_load_lds_dwordx4 v[140:141], off
	s_waitcnt vmcnt(8)
	s_waitcnt lgkmcnt(0)
	s_barrier
	s_setprio 1
	s_waitcnt lgkmcnt(0)
	v_mfma_f32_16x16x32_bf16 v[68:71], v[136:139], v[212:215], v[68:71]
	v_mfma_f32_16x16x32_bf16 v[64:67], v[172:175], v[212:215], v[64:67]
	v_mfma_f32_16x16x32_bf16 v[52:55], v[136:139], v[220:223], v[52:55]
	v_mfma_f32_16x16x32_bf16 v[48:51], v[172:175], v[220:223], v[48:51]
	v_mfma_f32_16x16x32_bf16 v[28:31], v[136:139], v[228:231], v[28:31]
	v_mfma_f32_16x16x32_bf16 v[24:27], v[172:175], v[228:231], v[24:27]
	v_mfma_f32_16x16x32_bf16 v[12:15], v[136:139], v[236:239], v[12:15]
	v_mfma_f32_16x16x32_bf16 v[8:11], v[172:175], v[236:239], v[8:11]
	v_mfma_f32_16x16x32_bf16 v[68:71], v[158:161], v[216:219], v[68:71]
	v_mfma_f32_16x16x32_bf16 v[64:67], v[192:195], v[216:219], v[64:67]
	v_mfma_f32_16x16x32_bf16 v[52:55], v[158:161], v[224:227], v[52:55]
	v_mfma_f32_16x16x32_bf16 v[48:51], v[192:195], v[224:227], v[48:51]
	v_mfma_f32_16x16x32_bf16 v[28:31], v[158:161], v[232:235], v[28:31]
	v_mfma_f32_16x16x32_bf16 v[24:27], v[192:195], v[232:235], v[24:27]
	v_mfma_f32_16x16x32_bf16 v[12:15], v[158:161], v[240:243], v[12:15]
	v_mfma_f32_16x16x32_bf16 v[8:11], v[192:195], v[240:243], v[8:11]
	v_mfma_f32_16x16x32_bf16 v[60:63], v[196:199], v[212:215], v[60:63]
	v_mfma_f32_16x16x32_bf16 v[56:59], v[204:207], v[212:215], v[56:59]
	v_mfma_f32_16x16x32_bf16 v[44:47], v[196:199], v[220:223], v[44:47]
	v_mfma_f32_16x16x32_bf16 v[40:43], v[204:207], v[220:223], v[40:43]
	v_mfma_f32_16x16x32_bf16 v[20:23], v[196:199], v[228:231], v[20:23]
	v_mfma_f32_16x16x32_bf16 v[16:19], v[204:207], v[228:231], v[16:19]
	v_mfma_f32_16x16x32_bf16 v[4:7], v[196:199], v[236:239], v[4:7]
	v_mfma_f32_16x16x32_bf16 v[0:3], v[204:207], v[236:239], v[0:3]
	v_mfma_f32_16x16x32_bf16 v[60:63], v[200:203], v[216:219], v[60:63]
	v_mfma_f32_16x16x32_bf16 v[56:59], v[208:211], v[216:219], v[56:59]
	v_mfma_f32_16x16x32_bf16 v[44:47], v[200:203], v[224:227], v[44:47]
	v_mfma_f32_16x16x32_bf16 v[40:43], v[208:211], v[224:227], v[40:43]
	v_mfma_f32_16x16x32_bf16 v[20:23], v[200:203], v[232:235], v[20:23]
	v_mfma_f32_16x16x32_bf16 v[16:19], v[208:211], v[232:235], v[16:19]
	v_mfma_f32_16x16x32_bf16 v[4:7], v[200:203], v[240:243], v[4:7]
	v_mfma_f32_16x16x32_bf16 v[0:3], v[208:211], v[240:243], v[0:3]
	s_setprio 0
	s_barrier
	s_add_i32 s58, s58, 2
	s_add_u32 s30, s30, 0x100
	s_addc_u32 s31, s31, 0
	s_add_u32 s56, s56, 0x100
	s_addc_u32 s57, s57, 0
	s_cmp_gt_u32 s58, 29
	s_cbranch_scc0 .LBB0_822
	s_and_b64 vcc, exec, s[2:3]
	s_cbranch_vccz .LBB0_825
	s_barrier

.LBB0_854:
	s_add_i32 s79, s24, 2
	s_add_u32 s26, s28, 0x80
	s_addc_u32 s25, s29, 0
	s_add_i32 s82, 0, 0x10000
	s_cmp_eq_u32 s59, s24
	s_cselect_b32 s25, s1, s25
	s_cselect_b32 s24, s0, s26
	v_add_u32_e32 v140, s82, v160
	s_cselect_b32 s81, s47, s31
	s_cselect_b32 s80, s46, s30
	s_add_i32 s26, 0, 0x14000
	ds_read_b128 v[136:139], v140
	ds_read_b128 v[154:157], v140 offset:1024
	ds_read_b128 v[172:175], v140 offset:2048
	ds_read_b128 v[192:195], v140 offset:3072
	v_add_u32_e32 v140, s26, v160
	ds_read_b128 v[196:199], v140
	ds_read_b128 v[200:203], v140 offset:1024
	ds_read_b128 v[204:207], v140 offset:2048
	ds_read_b128 v[208:211], v140 offset:3072
	v_lshl_add_u64 v[140:141], s[28:29], 0, v[150:151]
	s_add_i32 m0, s51, 0xc000
	ds_read_b128 v[212:215], v162
	ds_read_b128 v[216:219], v162 offset:1024
	ds_read_b128 v[220:223], v162 offset:2048
	ds_read_b128 v[224:227], v162 offset:3072
	ds_read_b128 v[228:231], v162 offset:4096
	ds_read_b128 v[232:235], v162 offset:5120
	ds_read_b128 v[236:239], v162 offset:6144
	ds_read_b128 v[240:243], v162 offset:7168
	global_load_lds_dwordx4 v[140:141], off
	v_lshl_add_u64 v[140:141], s[28:29], 0, v[152:153]
	s_add_i32 m0, s51, 0xe000
	s_nop 0
	global_load_lds_dwordx4 v[140:141], off
	s_waitcnt vmcnt(8)
	s_waitcnt lgkmcnt(0)
	s_barrier
	s_setprio 1
	s_waitcnt lgkmcnt(0)
	v_mfma_f32_16x16x32_bf16 v[132:135], v[136:139], v[212:215], v[132:135]
	v_mfma_f32_16x16x32_bf16 v[128:131], v[172:175], v[212:215], v[128:131]
	v_mfma_f32_16x16x32_bf16 v[116:119], v[136:139], v[220:223], v[116:119]
	v_mfma_f32_16x16x32_bf16 v[112:115], v[172:175], v[220:223], v[112:115]
	v_mfma_f32_16x16x32_bf16 v[100:103], v[136:139], v[228:231], v[100:103]
	v_mfma_f32_16x16x32_bf16 v[96:99], v[172:175], v[228:231], v[96:99]
	v_mfma_f32_16x16x32_bf16 v[84:87], v[136:139], v[236:239], v[84:87]
	v_mfma_f32_16x16x32_bf16 v[80:83], v[172:175], v[236:239], v[80:83]
	v_mfma_f32_16x16x32_bf16 v[132:135], v[154:157], v[216:219], v[132:135]
	v_mfma_f32_16x16x32_bf16 v[128:131], v[192:195], v[216:219], v[128:131]
	v_mfma_f32_16x16x32_bf16 v[116:119], v[154:157], v[224:227], v[116:119]
	v_mfma_f32_16x16x32_bf16 v[112:115], v[192:195], v[224:227], v[112:115]
	v_mfma_f32_16x16x32_bf16 v[100:103], v[154:157], v[232:235], v[100:103]
	v_mfma_f32_16x16x32_bf16 v[96:99], v[192:195], v[232:235], v[96:99]
	v_mfma_f32_16x16x32_bf16 v[84:87], v[154:157], v[240:243], v[84:87]
	v_mfma_f32_16x16x32_bf16 v[80:83], v[192:195], v[240:243], v[80:83]
	v_mfma_f32_16x16x32_bf16 v[124:127], v[196:199], v[212:215], v[124:127]
	v_mfma_f32_16x16x32_bf16 v[120:123], v[204:207], v[212:215], v[120:123]
	v_mfma_f32_16x16x32_bf16 v[108:111], v[196:199], v[220:223], v[108:111]
	v_mfma_f32_16x16x32_bf16 v[104:107], v[204:207], v[220:223], v[104:107]
	v_mfma_f32_16x16x32_bf16 v[92:95], v[196:199], v[228:231], v[92:95]
	v_mfma_f32_16x16x32_bf16 v[88:91], v[204:207], v[228:231], v[88:91]
	v_mfma_f32_16x16x32_bf16 v[76:79], v[196:199], v[236:239], v[76:79]
	v_mfma_f32_16x16x32_bf16 v[72:75], v[204:207], v[236:239], v[72:75]
	v_mfma_f32_16x16x32_bf16 v[124:127], v[200:203], v[216:219], v[124:127]
	v_mfma_f32_16x16x32_bf16 v[120:123], v[208:211], v[216:219], v[120:123]
	v_mfma_f32_16x16x32_bf16 v[108:111], v[200:203], v[224:227], v[108:111]
	v_mfma_f32_16x16x32_bf16 v[104:107], v[208:211], v[224:227], v[104:107]
	v_mfma_f32_16x16x32_bf16 v[92:95], v[200:203], v[232:235], v[92:95]
	v_mfma_f32_16x16x32_bf16 v[88:91], v[208:211], v[232:235], v[88:91]
	v_mfma_f32_16x16x32_bf16 v[76:79], v[200:203], v[240:243], v[76:79]
	v_mfma_f32_16x16x32_bf16 v[72:75], v[208:211], v[240:243], v[72:75]
	s_setprio 0
	s_barrier
	s_add_i32 s82, s82, s50
	v_lshl_add_u64 v[140:141], s[80:81], 0, v[144:145]
	s_mov_b32 m0, s82
	ds_read_b128 v[212:215], v162 offset:16384
	ds_read_b128 v[216:219], v162 offset:17408
	ds_read_b128 v[220:223], v162 offset:18432
	ds_read_b128 v[224:227], v162 offset:19456
	ds_read_b128 v[228:231], v162 offset:20480
	ds_read_b128 v[232:235], v162 offset:21504
	ds_read_b128 v[236:239], v162 offset:22528
	ds_read_b128 v[240:243], v162 offset:23552
	global_load_lds_dwordx4 v[140:141], off
	s_add_i32 m0, s82, 0x2000
	v_lshl_add_u64 v[142:143], s[80:81], 0, v[148:149]
	s_add_u32 s80, s80, s2
	s_addc_u32 s81, s81, 0
	s_add_i32 s26, s26, s50
	global_load_lds_dwordx4 v[142:143], off
	v_lshl_add_u64 v[158:159], s[80:81], 0, v[144:145]
	s_mov_b32 m0, s26
	v_lshl_add_u64 v[168:169], s[80:81], 0, v[148:149]
	global_load_lds_dwordx4 v[158:159], off
	s_add_i32 m0, s26, 0x2000
	v_lshl_add_u64 v[176:177], s[24:25], 0, v[34:35]
	global_load_lds_dwordx4 v[168:169], off
	s_mov_b32 m0, s51
	v_lshl_add_u64 v[244:245], s[24:25], 0, v[146:147]
	global_load_lds_dwordx4 v[176:177], off
	s_mov_b32 m0, s52
	s_nop 0
	global_load_lds_dwordx4 v[244:245], off
	s_waitcnt vmcnt(8)
	s_waitcnt lgkmcnt(0)
	s_barrier
	s_setprio 1
	s_waitcnt lgkmcnt(0)
	v_mfma_f32_16x16x32_bf16 v[68:71], v[136:139], v[212:215], v[68:71]
	v_mfma_f32_16x16x32_bf16 v[64:67], v[172:175], v[212:215], v[64:67]
	v_mfma_f32_16x16x32_bf16 v[52:55], v[136:139], v[220:223], v[52:55]
	v_mfma_f32_16x16x32_bf16 v[48:51], v[172:175], v[220:223], v[48:51]
	v_mfma_f32_16x16x32_bf16 v[28:31], v[136:139], v[228:231], v[28:31]
	v_mfma_f32_16x16x32_bf16 v[24:27], v[172:175], v[228:231], v[24:27]
	v_mfma_f32_16x16x32_bf16 v[12:15], v[136:139], v[236:239], v[12:15]
	v_mfma_f32_16x16x32_bf16 v[8:11], v[172:175], v[236:239], v[8:11]
	v_mfma_f32_16x16x32_bf16 v[68:71], v[154:157], v[216:219], v[68:71]
	v_mfma_f32_16x16x32_bf16 v[64:67], v[192:195], v[216:219], v[64:67]
	v_mfma_f32_16x16x32_bf16 v[52:55], v[154:157], v[224:227], v[52:55]
	v_mfma_f32_16x16x32_bf16 v[48:51], v[192:195], v[224:227], v[48:51]
	v_mfma_f32_16x16x32_bf16 v[28:31], v[154:157], v[232:235], v[28:31]
	v_mfma_f32_16x16x32_bf16 v[24:27], v[192:195], v[232:235], v[24:27]
	v_mfma_f32_16x16x32_bf16 v[12:15], v[154:157], v[240:243], v[12:15]
	v_mfma_f32_16x16x32_bf16 v[8:11], v[192:195], v[240:243], v[8:11]
	v_mfma_f32_16x16x32_bf16 v[60:63], v[196:199], v[212:215], v[60:63]
	v_mfma_f32_16x16x32_bf16 v[56:59], v[204:207], v[212:215], v[56:59]
	v_mfma_f32_16x16x32_bf16 v[44:47], v[196:199], v[220:223], v[44:47]
	v_mfma_f32_16x16x32_bf16 v[40:43], v[204:207], v[220:223], v[40:43]
	v_mfma_f32_16x16x32_bf16 v[20:23], v[196:199], v[228:231], v[20:23]
	v_mfma_f32_16x16x32_bf16 v[16:19], v[204:207], v[228:231], v[16:19]
	v_mfma_f32_16x16x32_bf16 v[4:7], v[196:199], v[236:239], v[4:7]
	v_mfma_f32_16x16x32_bf16 v[0:3], v[204:207], v[236:239], v[0:3]
	v_mfma_f32_16x16x32_bf16 v[60:63], v[200:203], v[216:219], v[60:63]
	v_mfma_f32_16x16x32_bf16 v[56:59], v[208:211], v[216:219], v[56:59]
	v_mfma_f32_16x16x32_bf16 v[44:47], v[200:203], v[224:227], v[44:47]
	v_mfma_f32_16x16x32_bf16 v[40:43], v[208:211], v[224:227], v[40:43]
	v_mfma_f32_16x16x32_bf16 v[20:23], v[200:203], v[232:235], v[20:23]
	v_mfma_f32_16x16x32_bf16 v[16:19], v[208:211], v[232:235], v[16:19]
	v_mfma_f32_16x16x32_bf16 v[4:7], v[200:203], v[240:243], v[4:7]
	v_mfma_f32_16x16x32_bf16 v[0:3], v[208:211], v[240:243], v[0:3]
	s_setprio 0
	s_barrier
	s_add_i32 s26, 0, 0x18000
	v_add_u32_e32 v163, s26, v160
	s_add_i32 s80, 0, 0x1c000
	ds_read_b128 v[136:139], v163
	ds_read_b128 v[154:157], v163 offset:1024
	ds_read_b128 v[172:175], v163 offset:2048
	ds_read_b128 v[192:195], v163 offset:3072
	v_add_u32_e32 v163, s80, v160
	ds_read_b128 v[196:199], v163
	ds_read_b128 v[200:203], v163 offset:1024
	ds_read_b128 v[204:207], v163 offset:2048
	ds_read_b128 v[208:211], v163 offset:3072
	s_add_u32 s24, s24, s2
	s_addc_u32 s25, s25, 0
	s_mov_b32 m0, s53
	v_lshl_add_u64 v[246:247], s[24:25], 0, v[34:35]
	ds_read_b128 v[212:215], v162 offset:32768
	ds_read_b128 v[216:219], v162 offset:33792
	ds_read_b128 v[220:223], v162 offset:34816
	ds_read_b128 v[224:227], v162 offset:35840
	ds_read_b128 v[228:231], v162 offset:36864
	ds_read_b128 v[232:235], v162 offset:37888
	ds_read_b128 v[236:239], v162 offset:38912
	ds_read_b128 v[240:243], v162 offset:39936
	global_load_lds_dwordx4 v[246:247], off
	v_lshl_add_u64 v[246:247], s[24:25], 0, v[146:147]
	s_mov_b32 m0, s54
	s_nop 0
	global_load_lds_dwordx4 v[246:247], off
	s_waitcnt vmcnt(8)
	s_waitcnt lgkmcnt(0)
	s_barrier
	s_setprio 1
	s_waitcnt lgkmcnt(0)
	v_mfma_f32_16x16x32_bf16 v[132:135], v[136:139], v[212:215], v[132:135]
	v_mfma_f32_16x16x32_bf16 v[128:131], v[172:175], v[212:215], v[128:131]
	v_mfma_f32_16x16x32_bf16 v[116:119], v[136:139], v[220:223], v[116:119]
	v_mfma_f32_16x16x32_bf16 v[112:115], v[172:175], v[220:223], v[112:115]
	v_mfma_f32_16x16x32_bf16 v[100:103], v[136:139], v[228:231], v[100:103]
	v_mfma_f32_16x16x32_bf16 v[96:99], v[172:175], v[228:231], v[96:99]
	v_mfma_f32_16x16x32_bf16 v[84:87], v[136:139], v[236:239], v[84:87]
	v_mfma_f32_16x16x32_bf16 v[80:83], v[172:175], v[236:239], v[80:83]
	v_mfma_f32_16x16x32_bf16 v[132:135], v[154:157], v[216:219], v[132:135]
	v_mfma_f32_16x16x32_bf16 v[128:131], v[192:195], v[216:219], v[128:131]
	v_mfma_f32_16x16x32_bf16 v[116:119], v[154:157], v[224:227], v[116:119]
	v_mfma_f32_16x16x32_bf16 v[112:115], v[192:195], v[224:227], v[112:115]
	v_mfma_f32_16x16x32_bf16 v[100:103], v[154:157], v[232:235], v[100:103]
	v_mfma_f32_16x16x32_bf16 v[96:99], v[192:195], v[232:235], v[96:99]
	v_mfma_f32_16x16x32_bf16 v[84:87], v[154:157], v[240:243], v[84:87]
	v_mfma_f32_16x16x32_bf16 v[80:83], v[192:195], v[240:243], v[80:83]
	v_mfma_f32_16x16x32_bf16 v[124:127], v[196:199], v[212:215], v[124:127]
	v_mfma_f32_16x16x32_bf16 v[120:123], v[204:207], v[212:215], v[120:123]
	v_mfma_f32_16x16x32_bf16 v[108:111], v[196:199], v[220:223], v[108:111]
	v_mfma_f32_16x16x32_bf16 v[104:107], v[204:207], v[220:223], v[104:107]
	v_mfma_f32_16x16x32_bf16 v[92:95], v[196:199], v[228:231], v[92:95]
	v_mfma_f32_16x16x32_bf16 v[88:91], v[204:207], v[228:231], v[88:91]
	v_mfma_f32_16x16x32_bf16 v[76:79], v[196:199], v[236:239], v[76:79]
	v_mfma_f32_16x16x32_bf16 v[72:75], v[204:207], v[236:239], v[72:75]
	v_mfma_f32_16x16x32_bf16 v[124:127], v[200:203], v[216:219], v[124:127]
	v_mfma_f32_16x16x32_bf16 v[120:123], v[208:211], v[216:219], v[120:123]
	v_mfma_f32_16x16x32_bf16 v[108:111], v[200:203], v[224:227], v[108:111]
	v_mfma_f32_16x16x32_bf16 v[104:107], v[208:211], v[224:227], v[104:107]
	v_mfma_f32_16x16x32_bf16 v[92:95], v[200:203], v[232:235], v[92:95]
	v_mfma_f32_16x16x32_bf16 v[88:91], v[208:211], v[232:235], v[88:91]
	v_mfma_f32_16x16x32_bf16 v[76:79], v[200:203], v[240:243], v[76:79]
	v_mfma_f32_16x16x32_bf16 v[72:75], v[208:211], v[240:243], v[72:75]
	s_setprio 0
	s_barrier
	s_add_i32 s24, s26, s50
	v_lshl_add_u64 v[140:141], v[140:141], 0, s[60:61]
	s_mov_b32 m0, s24
	ds_read_b128 v[212:215], v162 offset:49152
	ds_read_b128 v[216:219], v162 offset:50176
	ds_read_b128 v[220:223], v162 offset:51200
	ds_read_b128 v[224:227], v162 offset:52224
	ds_read_b128 v[228:231], v162 offset:53248
	ds_read_b128 v[232:235], v162 offset:54272
	ds_read_b128 v[236:239], v162 offset:55296
	ds_read_b128 v[240:243], v162 offset:56320
	global_load_lds_dwordx4 v[140:141], off
	v_lshl_add_u64 v[140:141], v[142:143], 0, s[60:61]
	s_add_i32 m0, s24, 0x2000
	s_add_i32 s24, s80, s50
	global_load_lds_dwordx4 v[140:141], off
	v_lshl_add_u64 v[140:141], v[158:159], 0, s[60:61]
	s_mov_b32 m0, s24
	s_nop 0
	global_load_lds_dwordx4 v[140:141], off
	v_lshl_add_u64 v[140:141], v[168:169], 0, s[60:61]
	s_add_i32 m0, s24, 0x2000
	s_nop 0
	global_load_lds_dwordx4 v[140:141], off
	v_lshl_add_u64 v[140:141], v[176:177], 0, s[60:61]
	s_mov_b32 m0, s57
	s_nop 0
	global_load_lds_dwordx4 v[140:141], off
	v_lshl_add_u64 v[140:141], v[244:245], 0, s[60:61]
	s_mov_b32 m0, s58
	s_nop 0
	global_load_lds_dwordx4 v[140:141], off
	s_waitcnt vmcnt(8)
	s_waitcnt lgkmcnt(0)
	s_barrier
	s_setprio 1
	s_waitcnt lgkmcnt(0)
	v_mfma_f32_16x16x32_bf16 v[68:71], v[136:139], v[212:215], v[68:71]
	v_mfma_f32_16x16x32_bf16 v[64:67], v[172:175], v[212:215], v[64:67]
	v_mfma_f32_16x16x32_bf16 v[52:55], v[136:139], v[220:223], v[52:55]
	v_mfma_f32_16x16x32_bf16 v[48:51], v[172:175], v[220:223], v[48:51]
	v_mfma_f32_16x16x32_bf16 v[28:31], v[136:139], v[228:231], v[28:31]
	v_mfma_f32_16x16x32_bf16 v[24:27], v[172:175], v[228:231], v[24:27]
	v_mfma_f32_16x16x32_bf16 v[12:15], v[136:139], v[236:239], v[12:15]
	v_mfma_f32_16x16x32_bf16 v[8:11], v[172:175], v[236:239], v[8:11]
	v_mfma_f32_16x16x32_bf16 v[68:71], v[154:157], v[216:219], v[68:71]
	v_mfma_f32_16x16x32_bf16 v[64:67], v[192:195], v[216:219], v[64:67]
	v_mfma_f32_16x16x32_bf16 v[52:55], v[154:157], v[224:227], v[52:55]
	v_mfma_f32_16x16x32_bf16 v[48:51], v[192:195], v[224:227], v[48:51]
	v_mfma_f32_16x16x32_bf16 v[28:31], v[154:157], v[232:235], v[28:31]
	v_mfma_f32_16x16x32_bf16 v[24:27], v[192:195], v[232:235], v[24:27]
	v_mfma_f32_16x16x32_bf16 v[12:15], v[154:157], v[240:243], v[12:15]
	v_mfma_f32_16x16x32_bf16 v[8:11], v[192:195], v[240:243], v[8:11]
	v_mfma_f32_16x16x32_bf16 v[60:63], v[196:199], v[212:215], v[60:63]
	v_mfma_f32_16x16x32_bf16 v[56:59], v[204:207], v[212:215], v[56:59]
	v_mfma_f32_16x16x32_bf16 v[44:47], v[196:199], v[220:223], v[44:47]
	v_mfma_f32_16x16x32_bf16 v[40:43], v[204:207], v[220:223], v[40:43]
	v_mfma_f32_16x16x32_bf16 v[20:23], v[196:199], v[228:231], v[20:23]
	v_mfma_f32_16x16x32_bf16 v[16:19], v[204:207], v[228:231], v[16:19]
	v_mfma_f32_16x16x32_bf16 v[4:7], v[196:199], v[236:239], v[4:7]
	v_mfma_f32_16x16x32_bf16 v[0:3], v[204:207], v[236:239], v[0:3]
	v_mfma_f32_16x16x32_bf16 v[60:63], v[200:203], v[216:219], v[60:63]
	v_mfma_f32_16x16x32_bf16 v[56:59], v[208:211], v[216:219], v[56:59]
	v_mfma_f32_16x16x32_bf16 v[44:47], v[200:203], v[224:227], v[44:47]
	v_mfma_f32_16x16x32_bf16 v[40:43], v[208:211], v[224:227], v[40:43]
	v_mfma_f32_16x16x32_bf16 v[20:23], v[200:203], v[232:235], v[20:23]
	v_mfma_f32_16x16x32_bf16 v[16:19], v[208:211], v[232:235], v[16:19]
	v_mfma_f32_16x16x32_bf16 v[4:7], v[200:203], v[240:243], v[4:7]
	v_mfma_f32_16x16x32_bf16 v[0:3], v[208:211], v[240:243], v[0:3]
	s_setprio 0
	s_barrier
	s_add_u32 s28, s28, 0x100
	s_addc_u32 s29, s29, 0
	s_add_u32 s30, s30, 0x100
	s_addc_u32 s31, s31, 0
	s_cmp_ge_u32 s79, s56
	s_mov_b32 s24, s79
	s_cbranch_scc0 .LBB0_854
	s_and_b64 vcc, exec, s[44:45]
	s_cbranch_vccz .LBB0_857
	s_barrier

.LBB0_899:
	s_add_i32 vcc_lo, s24, 2
	s_add_u32 s28, s0, 0x80
	s_addc_u32 s25, s1, 0
	s_add_i32 vcc_hi, 0, 0x10000
	s_cmp_eq_u32 s85, s24
	s_cselect_b32 s25, s51, s25
	s_cselect_b32 s24, s50, s28
	v_add_u32_e32 v136, vcc_hi, v157
	s_cselect_b32 s29, s69, s71
	s_cselect_b32 s28, s68, s70
	s_add_i32 s26, 0, 0x14000
	ds_read_b128 v[192:195], v136
	ds_read_b128 v[196:199], v136 offset:1024
	ds_read_b128 v[200:203], v136 offset:2048
	ds_read_b128 v[204:207], v136 offset:3072
	v_add_u32_e32 v136, s26, v157
	ds_read_b128 v[208:211], v136
	ds_read_b128 v[212:215], v136 offset:1024
	ds_read_b128 v[216:219], v136 offset:2048
	ds_read_b128 v[220:223], v136 offset:3072
	v_lshl_add_u64 v[154:155], s[0:1], 0, v[150:151]
	s_add_i32 m0, s82, 0xc000
	ds_read_b128 v[224:227], v161
	ds_read_b128 v[228:231], v161 offset:1024
	ds_read_b128 v[232:235], v161 offset:2048
	ds_read_b128 v[236:239], v161 offset:3072
	ds_read_b128 v[240:243], v161 offset:4096
	ds_read_b128 v[244:247], v161 offset:5120
	ds_read_b128 v[136:139], v161 offset:6144
	ds_read_b128 v[172:175], v161 offset:7168
	global_load_lds_dwordx4 v[154:155], off
	v_lshl_add_u64 v[154:155], s[0:1], 0, v[152:153]
	s_add_i32 m0, s82, 0xe000
	s_nop 0
	global_load_lds_dwordx4 v[154:155], off
	s_waitcnt vmcnt(8)
	s_waitcnt lgkmcnt(0)
	s_barrier
	s_setprio 1
	s_waitcnt lgkmcnt(0)
	v_mfma_f32_16x16x32_bf16 v[132:135], v[192:195], v[224:227], v[132:135]
	v_mfma_f32_16x16x32_bf16 v[128:131], v[200:203], v[224:227], v[128:131]
	v_mfma_f32_16x16x32_bf16 v[124:127], v[192:195], v[232:235], v[124:127]
	v_mfma_f32_16x16x32_bf16 v[116:119], v[200:203], v[232:235], v[116:119]
	v_mfma_f32_16x16x32_bf16 v[108:111], v[192:195], v[240:243], v[108:111]
	v_mfma_f32_16x16x32_bf16 v[100:103], v[200:203], v[240:243], v[100:103]
	v_mfma_f32_16x16x32_bf16 v[92:95], v[192:195], v[136:139], v[92:95]
	v_mfma_f32_16x16x32_bf16 v[84:87], v[200:203], v[136:139], v[84:87]
	v_mfma_f32_16x16x32_bf16 v[132:135], v[196:199], v[228:231], v[132:135]
	v_mfma_f32_16x16x32_bf16 v[128:131], v[204:207], v[228:231], v[128:131]
	v_mfma_f32_16x16x32_bf16 v[124:127], v[196:199], v[236:239], v[124:127]
	v_mfma_f32_16x16x32_bf16 v[116:119], v[204:207], v[236:239], v[116:119]
	v_mfma_f32_16x16x32_bf16 v[108:111], v[196:199], v[244:247], v[108:111]
	v_mfma_f32_16x16x32_bf16 v[100:103], v[204:207], v[244:247], v[100:103]
	v_mfma_f32_16x16x32_bf16 v[92:95], v[196:199], v[172:175], v[92:95]
	v_mfma_f32_16x16x32_bf16 v[84:87], v[204:207], v[172:175], v[84:87]
	v_mfma_f32_16x16x32_bf16 v[120:123], v[208:211], v[224:227], v[120:123]
	v_mfma_f32_16x16x32_bf16 v[112:115], v[216:219], v[224:227], v[112:115]
	v_mfma_f32_16x16x32_bf16 v[104:107], v[208:211], v[232:235], v[104:107]
	v_mfma_f32_16x16x32_bf16 v[96:99], v[216:219], v[232:235], v[96:99]
	v_mfma_f32_16x16x32_bf16 v[88:91], v[208:211], v[240:243], v[88:91]
	v_mfma_f32_16x16x32_bf16 v[80:83], v[216:219], v[240:243], v[80:83]
	v_mfma_f32_16x16x32_bf16 v[76:79], v[208:211], v[136:139], v[76:79]
	v_mfma_f32_16x16x32_bf16 v[72:75], v[216:219], v[136:139], v[72:75]
	v_mfma_f32_16x16x32_bf16 v[120:123], v[212:215], v[228:231], v[120:123]
	v_mfma_f32_16x16x32_bf16 v[112:115], v[220:223], v[228:231], v[112:115]
	v_mfma_f32_16x16x32_bf16 v[104:107], v[212:215], v[236:239], v[104:107]
	v_mfma_f32_16x16x32_bf16 v[96:99], v[220:223], v[236:239], v[96:99]
	v_mfma_f32_16x16x32_bf16 v[88:91], v[212:215], v[244:247], v[88:91]
	v_mfma_f32_16x16x32_bf16 v[80:83], v[220:223], v[244:247], v[80:83]
	v_mfma_f32_16x16x32_bf16 v[76:79], v[212:215], v[172:175], v[76:79]
	v_mfma_f32_16x16x32_bf16 v[72:75], v[220:223], v[172:175], v[72:75]
	s_setprio 0
	s_barrier
	s_add_i32 vcc_hi, vcc_hi, s81
	v_lshl_add_u64 v[154:155], s[28:29], 0, v[144:145]
	s_mov_b32 m0, vcc_hi
	ds_read_b128 v[136:139], v161 offset:16384
	ds_read_b128 v[172:175], v161 offset:17408
	ds_read_b128 v[224:227], v161 offset:18432
	ds_read_b128 v[228:231], v161 offset:19456
	ds_read_b128 v[232:235], v161 offset:20480
	ds_read_b128 v[236:239], v161 offset:21504
	ds_read_b128 v[240:243], v161 offset:22528
	ds_read_b128 v[244:247], v161 offset:23552
	global_load_lds_dwordx4 v[154:155], off
	s_add_i32 m0, vcc_hi, 0x2000
	v_lshl_add_u64 v[162:163], s[28:29], 0, v[148:149]
	s_add_u32 s28, s28, s39
	s_addc_u32 s29, s29, 0
	s_add_i32 s26, s26, s81
	global_load_lds_dwordx4 v[162:163], off
	v_lshl_add_u64 v[168:169], s[28:29], 0, v[144:145]
	s_mov_b32 m0, s26
	v_lshl_add_u64 v[176:177], s[28:29], 0, v[148:149]
	global_load_lds_dwordx4 v[168:169], off
	s_add_i32 m0, s26, 0x2000
	v_lshl_add_u64 v[248:249], s[24:25], 0, v[34:35]
	global_load_lds_dwordx4 v[176:177], off
	s_mov_b32 m0, s82
	v_lshl_add_u64 v[140:141], s[24:25], 0, v[146:147]
	global_load_lds_dwordx4 v[248:249], off
	s_mov_b32 m0, s83
	s_nop 0
	global_load_lds_dwordx4 v[140:141], off
	s_waitcnt vmcnt(8)
	s_waitcnt lgkmcnt(0)
	s_barrier
	s_setprio 1
	s_waitcnt lgkmcnt(0)
	v_mfma_f32_16x16x32_bf16 v[68:71], v[192:195], v[136:139], v[68:71]
	v_mfma_f32_16x16x32_bf16 v[64:67], v[200:203], v[136:139], v[64:67]
	v_mfma_f32_16x16x32_bf16 v[60:63], v[192:195], v[224:227], v[60:63]
	v_mfma_f32_16x16x32_bf16 v[52:55], v[200:203], v[224:227], v[52:55]
	v_mfma_f32_16x16x32_bf16 v[44:47], v[192:195], v[232:235], v[44:47]
	v_mfma_f32_16x16x32_bf16 v[28:31], v[200:203], v[232:235], v[28:31]
	v_mfma_f32_16x16x32_bf16 v[20:23], v[192:195], v[240:243], v[20:23]
	v_mfma_f32_16x16x32_bf16 v[12:15], v[200:203], v[240:243], v[12:15]
	v_mfma_f32_16x16x32_bf16 v[68:71], v[196:199], v[172:175], v[68:71]
	v_mfma_f32_16x16x32_bf16 v[64:67], v[204:207], v[172:175], v[64:67]
	v_mfma_f32_16x16x32_bf16 v[60:63], v[196:199], v[228:231], v[60:63]
	v_mfma_f32_16x16x32_bf16 v[52:55], v[204:207], v[228:231], v[52:55]
	v_mfma_f32_16x16x32_bf16 v[44:47], v[196:199], v[236:239], v[44:47]
	v_mfma_f32_16x16x32_bf16 v[28:31], v[204:207], v[236:239], v[28:31]
	v_mfma_f32_16x16x32_bf16 v[20:23], v[196:199], v[244:247], v[20:23]
	v_mfma_f32_16x16x32_bf16 v[12:15], v[204:207], v[244:247], v[12:15]
	v_mfma_f32_16x16x32_bf16 v[56:59], v[208:211], v[136:139], v[56:59]
	v_mfma_f32_16x16x32_bf16 v[48:51], v[216:219], v[136:139], v[48:51]
	v_mfma_f32_16x16x32_bf16 v[40:43], v[208:211], v[224:227], v[40:43]
	v_mfma_f32_16x16x32_bf16 v[24:27], v[216:219], v[224:227], v[24:27]
	v_mfma_f32_16x16x32_bf16 v[16:19], v[208:211], v[232:235], v[16:19]
	v_mfma_f32_16x16x32_bf16 v[8:11], v[216:219], v[232:235], v[8:11]
	v_mfma_f32_16x16x32_bf16 v[4:7], v[208:211], v[240:243], v[4:7]
	v_mfma_f32_16x16x32_bf16 v[0:3], v[216:219], v[240:243], v[0:3]
	v_mfma_f32_16x16x32_bf16 v[56:59], v[212:215], v[172:175], v[56:59]
	v_mfma_f32_16x16x32_bf16 v[48:51], v[220:223], v[172:175], v[48:51]
	v_mfma_f32_16x16x32_bf16 v[40:43], v[212:215], v[228:231], v[40:43]
	v_mfma_f32_16x16x32_bf16 v[24:27], v[220:223], v[228:231], v[24:27]
	v_mfma_f32_16x16x32_bf16 v[16:19], v[212:215], v[236:239], v[16:19]
	v_mfma_f32_16x16x32_bf16 v[8:11], v[220:223], v[236:239], v[8:11]
	v_mfma_f32_16x16x32_bf16 v[4:7], v[212:215], v[244:247], v[4:7]
	v_mfma_f32_16x16x32_bf16 v[0:3], v[220:223], v[244:247], v[0:3]
	s_setprio 0
	s_barrier
	s_add_i32 s26, 0, 0x18000
	v_add_u32_e32 v142, s26, v157
	s_add_i32 s28, 0, 0x1c000
	ds_read_b128 v[136:139], v142
	ds_read_b128 v[172:175], v142 offset:1024
	ds_read_b128 v[192:195], v142 offset:2048
	ds_read_b128 v[196:199], v142 offset:3072
	v_add_u32_e32 v142, s28, v157
	ds_read_b128 v[200:203], v142
	ds_read_b128 v[204:207], v142 offset:1024
	ds_read_b128 v[208:211], v142 offset:2048
	ds_read_b128 v[212:215], v142 offset:3072
	s_add_u32 s24, s24, s76
	s_addc_u32 s25, s25, 0
	s_mov_b32 m0, s86
	v_lshl_add_u64 v[142:143], s[24:25], 0, v[34:35]
	ds_read_b128 v[216:219], v161 offset:32768
	ds_read_b128 v[220:223], v161 offset:33792
	ds_read_b128 v[224:227], v161 offset:34816
	ds_read_b128 v[228:231], v161 offset:35840
	ds_read_b128 v[232:235], v161 offset:36864
	ds_read_b128 v[236:239], v161 offset:37888
	ds_read_b128 v[240:243], v161 offset:38912
	ds_read_b128 v[244:247], v161 offset:39936
	global_load_lds_dwordx4 v[142:143], off
	v_lshl_add_u64 v[142:143], s[24:25], 0, v[146:147]
	s_mov_b32 m0, s88
	s_nop 0
	global_load_lds_dwordx4 v[142:143], off
	s_waitcnt vmcnt(8)
	s_waitcnt lgkmcnt(0)
	s_barrier
	s_setprio 1
	s_waitcnt lgkmcnt(0)
	v_mfma_f32_16x16x32_bf16 v[132:135], v[136:139], v[216:219], v[132:135]
	v_mfma_f32_16x16x32_bf16 v[128:131], v[192:195], v[216:219], v[128:131]
	v_mfma_f32_16x16x32_bf16 v[124:127], v[136:139], v[224:227], v[124:127]
	v_mfma_f32_16x16x32_bf16 v[116:119], v[192:195], v[224:227], v[116:119]
	v_mfma_f32_16x16x32_bf16 v[108:111], v[136:139], v[232:235], v[108:111]
	v_mfma_f32_16x16x32_bf16 v[100:103], v[192:195], v[232:235], v[100:103]
	v_mfma_f32_16x16x32_bf16 v[92:95], v[136:139], v[240:243], v[92:95]
	v_mfma_f32_16x16x32_bf16 v[84:87], v[192:195], v[240:243], v[84:87]
	v_mfma_f32_16x16x32_bf16 v[132:135], v[172:175], v[220:223], v[132:135]
	v_mfma_f32_16x16x32_bf16 v[128:131], v[196:199], v[220:223], v[128:131]
	v_mfma_f32_16x16x32_bf16 v[124:127], v[172:175], v[228:231], v[124:127]
	v_mfma_f32_16x16x32_bf16 v[116:119], v[196:199], v[228:231], v[116:119]
	v_mfma_f32_16x16x32_bf16 v[108:111], v[172:175], v[236:239], v[108:111]
	v_mfma_f32_16x16x32_bf16 v[100:103], v[196:199], v[236:239], v[100:103]
	v_mfma_f32_16x16x32_bf16 v[92:95], v[172:175], v[244:247], v[92:95]
	v_mfma_f32_16x16x32_bf16 v[84:87], v[196:199], v[244:247], v[84:87]
	v_mfma_f32_16x16x32_bf16 v[120:123], v[200:203], v[216:219], v[120:123]
	v_mfma_f32_16x16x32_bf16 v[112:115], v[208:211], v[216:219], v[112:115]
	v_mfma_f32_16x16x32_bf16 v[104:107], v[200:203], v[224:227], v[104:107]
	v_mfma_f32_16x16x32_bf16 v[96:99], v[208:211], v[224:227], v[96:99]
	v_mfma_f32_16x16x32_bf16 v[88:91], v[200:203], v[232:235], v[88:91]
	v_mfma_f32_16x16x32_bf16 v[80:83], v[208:211], v[232:235], v[80:83]
	v_mfma_f32_16x16x32_bf16 v[76:79], v[200:203], v[240:243], v[76:79]
	v_mfma_f32_16x16x32_bf16 v[72:75], v[208:211], v[240:243], v[72:75]
	v_mfma_f32_16x16x32_bf16 v[120:123], v[204:207], v[220:223], v[120:123]
	v_mfma_f32_16x16x32_bf16 v[112:115], v[212:215], v[220:223], v[112:115]
	v_mfma_f32_16x16x32_bf16 v[104:107], v[204:207], v[228:231], v[104:107]
	v_mfma_f32_16x16x32_bf16 v[96:99], v[212:215], v[228:231], v[96:99]
	v_mfma_f32_16x16x32_bf16 v[88:91], v[204:207], v[236:239], v[88:91]
	v_mfma_f32_16x16x32_bf16 v[80:83], v[212:215], v[236:239], v[80:83]
	v_mfma_f32_16x16x32_bf16 v[76:79], v[204:207], v[244:247], v[76:79]
	v_mfma_f32_16x16x32_bf16 v[72:75], v[212:215], v[244:247], v[72:75]
	s_setprio 0
	s_barrier
	s_add_i32 s24, s26, s81
	v_lshl_add_u64 v[142:143], v[154:155], 0, s[60:61]
	s_mov_b32 m0, s24
	ds_read_b128 v[216:219], v161 offset:49152
	ds_read_b128 v[220:223], v161 offset:50176
	ds_read_b128 v[224:227], v161 offset:51200
	ds_read_b128 v[228:231], v161 offset:52224
	ds_read_b128 v[232:235], v161 offset:53248
	ds_read_b128 v[236:239], v161 offset:54272
	ds_read_b128 v[240:243], v161 offset:55296
	ds_read_b128 v[244:247], v161 offset:56320
	global_load_lds_dwordx4 v[142:143], off
	v_lshl_add_u64 v[142:143], v[162:163], 0, s[60:61]
	s_add_i32 m0, s24, 0x2000
	s_add_i32 s24, s28, s81
	global_load_lds_dwordx4 v[142:143], off
	v_lshl_add_u64 v[142:143], v[168:169], 0, s[60:61]
	s_mov_b32 m0, s24
	v_lshl_add_u64 v[140:141], v[140:141], 0, s[60:61]
	global_load_lds_dwordx4 v[142:143], off
	v_lshl_add_u64 v[142:143], v[176:177], 0, s[60:61]
	s_add_i32 m0, s24, 0x2000
	s_nop 0
	global_load_lds_dwordx4 v[142:143], off
	v_lshl_add_u64 v[142:143], v[248:249], 0, s[60:61]
	s_mov_b32 m0, s27
	s_nop 0
	global_load_lds_dwordx4 v[142:143], off
	s_mov_b32 m0, s44
	s_nop 0
	global_load_lds_dwordx4 v[140:141], off
	s_waitcnt vmcnt(8)
	s_waitcnt lgkmcnt(0)
	s_barrier
	s_setprio 1
	s_waitcnt lgkmcnt(0)
	v_mfma_f32_16x16x32_bf16 v[68:71], v[136:139], v[216:219], v[68:71]
	v_mfma_f32_16x16x32_bf16 v[64:67], v[192:195], v[216:219], v[64:67]
	v_mfma_f32_16x16x32_bf16 v[60:63], v[136:139], v[224:227], v[60:63]
	v_mfma_f32_16x16x32_bf16 v[52:55], v[192:195], v[224:227], v[52:55]
	v_mfma_f32_16x16x32_bf16 v[44:47], v[136:139], v[232:235], v[44:47]
	v_mfma_f32_16x16x32_bf16 v[28:31], v[192:195], v[232:235], v[28:31]
	v_mfma_f32_16x16x32_bf16 v[20:23], v[136:139], v[240:243], v[20:23]
	v_mfma_f32_16x16x32_bf16 v[12:15], v[192:195], v[240:243], v[12:15]
	v_mfma_f32_16x16x32_bf16 v[68:71], v[172:175], v[220:223], v[68:71]
	v_mfma_f32_16x16x32_bf16 v[64:67], v[196:199], v[220:223], v[64:67]
	v_mfma_f32_16x16x32_bf16 v[60:63], v[172:175], v[228:231], v[60:63]
	v_mfma_f32_16x16x32_bf16 v[52:55], v[196:199], v[228:231], v[52:55]
	v_mfma_f32_16x16x32_bf16 v[44:47], v[172:175], v[236:239], v[44:47]
	v_mfma_f32_16x16x32_bf16 v[28:31], v[196:199], v[236:239], v[28:31]
	v_mfma_f32_16x16x32_bf16 v[20:23], v[172:175], v[244:247], v[20:23]
	v_mfma_f32_16x16x32_bf16 v[12:15], v[196:199], v[244:247], v[12:15]
	v_mfma_f32_16x16x32_bf16 v[56:59], v[200:203], v[216:219], v[56:59]
	v_mfma_f32_16x16x32_bf16 v[48:51], v[208:211], v[216:219], v[48:51]
	v_mfma_f32_16x16x32_bf16 v[40:43], v[200:203], v[224:227], v[40:43]
	v_mfma_f32_16x16x32_bf16 v[24:27], v[208:211], v[224:227], v[24:27]
	v_mfma_f32_16x16x32_bf16 v[16:19], v[200:203], v[232:235], v[16:19]
	v_mfma_f32_16x16x32_bf16 v[8:11], v[208:211], v[232:235], v[8:11]
	v_mfma_f32_16x16x32_bf16 v[4:7], v[200:203], v[240:243], v[4:7]
	v_mfma_f32_16x16x32_bf16 v[0:3], v[208:211], v[240:243], v[0:3]
	v_mfma_f32_16x16x32_bf16 v[56:59], v[204:207], v[220:223], v[56:59]
	v_mfma_f32_16x16x32_bf16 v[48:51], v[212:215], v[220:223], v[48:51]
	v_mfma_f32_16x16x32_bf16 v[40:43], v[204:207], v[228:231], v[40:43]
	v_mfma_f32_16x16x32_bf16 v[24:27], v[212:215], v[228:231], v[24:27]
	v_mfma_f32_16x16x32_bf16 v[16:19], v[204:207], v[236:239], v[16:19]
	v_mfma_f32_16x16x32_bf16 v[8:11], v[212:215], v[236:239], v[8:11]
	v_mfma_f32_16x16x32_bf16 v[4:7], v[204:207], v[244:247], v[4:7]
	v_mfma_f32_16x16x32_bf16 v[0:3], v[212:215], v[244:247], v[0:3]
	s_setprio 0
	s_barrier
	s_add_u32 s0, s0, 0x100
	s_addc_u32 s1, s1, 0
	s_add_u32 s70, s70, 0x100
	s_addc_u32 s71, s71, 0
	s_cmp_ge_u32 vcc_lo, s22
	s_mov_b32 s24, vcc_lo
	s_cbranch_scc0 .LBB0_899
	s_and_b64 vcc, exec, s[34:35]
	s_cbranch_vccz .LBB0_902
	s_barrier
